# gate_up epilogue: row rstd values fetched before the K loop instead of at epilogue entry
# baseline (speedup 1.0000x reference)
;     __device__ __forceinline__ void operator()(const f32x4 (&acc)[2][2][4][2], const Unit& u, int wr, int wc, int fr, int fq) const {
;     ...
;             for (int m = 0; m < 4; ++m) rrv[ai][m] = rs[row0 + ai * HALF + m * 16];
; template <class Epi>
; __device__ __forceinline__ void gemm_phase(LAS unsigned char* lds, const Gemm g, const StaticOrder& S, const Epi& E) {
;     ...
;         for (int a = 0; a < 2; ++a)
; #pragma unroll
;             for (int b = 0; b < 2; ++b)
; #pragma unroll
;                 for (int m = 0; m < 4; ++m)
; #pragma unroll
;                     for (int n = 0; n < 2; ++n) acc[a][b][m][n] = (f32x4){0.f, 0.f, 0.f, 0.f};
.LBB0_1549:
	s_ashr_i32 s15, s14, 31
	s_lshl_b64 s[16:17], s[14:15], 19
	s_add_u32 s16, s27, s16
	s_addc_u32 s17, s28, s17
	s_and_b64 s[18:19], s[24:25], exec
	s_cselect_b32 s15, s17, s21
	s_cselect_b32 s46, s16, s20
	s_ashr_i32 s13, s12, 31
	s_lshl_b64 s[18:19], s[12:13], 19
	s_add_u32 s18, s29, s18
	s_addc_u32 s19, s30, s19
	s_and_b64 s[24:25], s[24:25], exec
	s_cselect_b32 s13, s19, s23
	s_cselect_b32 s47, s18, s22
	s_add_u32 s20, s20, 0x40080
	s_addc_u32 s21, s21, 0
	s_add_u32 s48, s22, 0x100
	v_mov_b32_e32 v2, 0
	s_addc_u32 s49, s23, 0
	s_mov_b32 s50, -2
	v_mov_b32_e32 v3, v2
	v_mov_b32_e32 v4, v2
	v_mov_b32_e32 v5, v2
	v_mov_b32_e32 v6, v2
	v_mov_b32_e32 v7, v2
	v_mov_b32_e32 v8, v2
	v_mov_b32_e32 v9, v2
	v_mov_b32_e32 v18, v2
	v_mov_b32_e32 v19, v2
	v_mov_b32_e32 v20, v2
	v_mov_b32_e32 v21, v2
	v_mov_b32_e32 v22, v2
	v_mov_b32_e32 v23, v2
	v_mov_b32_e32 v24, v2
	v_mov_b32_e32 v25, v2
	v_mov_b32_e32 v34, v2
	v_mov_b32_e32 v35, v2
	v_mov_b32_e32 v36, v2
	v_mov_b32_e32 v37, v2
	v_mov_b32_e32 v38, v2
	v_mov_b32_e32 v39, v2
	v_mov_b32_e32 v40, v2
	v_mov_b32_e32 v41, v2
	v_mov_b32_e32 v50, v2
	v_mov_b32_e32 v51, v2
	v_mov_b32_e32 v52, v2
	v_mov_b32_e32 v53, v2
	v_mov_b32_e32 v54, v2
	v_mov_b32_e32 v55, v2
	v_mov_b32_e32 v56, v2
	v_mov_b32_e32 v57, v2
	v_mov_b32_e32 v10, v2
	v_mov_b32_e32 v11, v2
	v_mov_b32_e32 v12, v2
	v_mov_b32_e32 v13, v2
	v_mov_b32_e32 v14, v2
	v_mov_b32_e32 v15, v2
	v_mov_b32_e32 v16, v2
	v_mov_b32_e32 v17, v2
	v_mov_b32_e32 v26, v2
	v_mov_b32_e32 v27, v2
	v_mov_b32_e32 v28, v2
	v_mov_b32_e32 v29, v2
	v_mov_b32_e32 v30, v2
	v_mov_b32_e32 v31, v2
	v_mov_b32_e32 v32, v2
	v_mov_b32_e32 v33, v2
	v_mov_b32_e32 v42, v2
	v_mov_b32_e32 v43, v2
	v_mov_b32_e32 v44, v2
	v_mov_b32_e32 v45, v2
	v_mov_b32_e32 v46, v2
	v_mov_b32_e32 v47, v2
	v_mov_b32_e32 v48, v2
	v_mov_b32_e32 v49, v2
	v_mov_b32_e32 v58, v2
	v_mov_b32_e32 v59, v2
	v_mov_b32_e32 v60, v2
	v_mov_b32_e32 v61, v2
	v_mov_b32_e32 v62, v2
	v_mov_b32_e32 v63, v2
	v_mov_b32_e32 v64, v2
	v_mov_b32_e32 v65, v2
	v_mov_b32_e32 v66, v2
	v_mov_b32_e32 v67, v2
	v_mov_b32_e32 v68, v2
	v_mov_b32_e32 v69, v2
	v_mov_b32_e32 v70, v2
	v_mov_b32_e32 v71, v2
	v_mov_b32_e32 v72, v2
	v_mov_b32_e32 v73, v2
	v_mov_b32_e32 v82, v2
	v_mov_b32_e32 v83, v2
	v_mov_b32_e32 v84, v2
	v_mov_b32_e32 v85, v2
	v_mov_b32_e32 v86, v2
	v_mov_b32_e32 v87, v2
	v_mov_b32_e32 v88, v2
	v_mov_b32_e32 v89, v2
	v_mov_b32_e32 v98, v2
	v_mov_b32_e32 v99, v2
	v_mov_b32_e32 v100, v2
	v_mov_b32_e32 v101, v2
	v_mov_b32_e32 v102, v2
	v_mov_b32_e32 v103, v2
	v_mov_b32_e32 v104, v2
	v_mov_b32_e32 v105, v2
	v_mov_b32_e32 v114, v2
	v_mov_b32_e32 v115, v2
	v_mov_b32_e32 v116, v2
	v_mov_b32_e32 v117, v2
	v_mov_b32_e32 v118, v2
	v_mov_b32_e32 v119, v2
	v_mov_b32_e32 v120, v2
	v_mov_b32_e32 v121, v2
	v_mov_b32_e32 v74, v2
	v_mov_b32_e32 v75, v2
	v_mov_b32_e32 v76, v2
	v_mov_b32_e32 v77, v2
	v_mov_b32_e32 v78, v2
	v_mov_b32_e32 v79, v2
	v_mov_b32_e32 v80, v2
	v_mov_b32_e32 v81, v2
	v_mov_b32_e32 v90, v2
	v_mov_b32_e32 v91, v2
	v_mov_b32_e32 v92, v2
	v_mov_b32_e32 v93, v2
	v_mov_b32_e32 v94, v2
	v_mov_b32_e32 v95, v2
	v_mov_b32_e32 v96, v2
	v_mov_b32_e32 v97, v2
	v_mov_b32_e32 v106, v2
	v_mov_b32_e32 v107, v2
	v_mov_b32_e32 v108, v2
	v_mov_b32_e32 v109, v2
	v_mov_b32_e32 v110, v2
	v_mov_b32_e32 v111, v2
	v_mov_b32_e32 v112, v2
	v_mov_b32_e32 v113, v2
	v_mov_b32_e32 v122, v2
	v_mov_b32_e32 v123, v2
	v_mov_b32_e32 v124, v2
	v_mov_b32_e32 v125, v2
	v_mov_b32_e32 v126, v2
	v_mov_b32_e32 v127, v2
	v_mov_b32_e32 v128, v2
	v_mov_b32_e32 v129, v2
	v_lshl_add_u32 v248, s45, 8, v1
	v_ashrrev_i32_e32 v249, 31, v248
	v_lshl_add_u64 v[248:249], v[248:249], 2, s[8:9]
	global_load_dword v240, v[248:249], off
	global_load_dword v241, v[248:249], off offset:64
	global_load_dword v242, v[248:249], off offset:128
	global_load_dword v243, v[248:249], off offset:192
	global_load_dword v244, v[248:249], off offset:512
	global_load_dword v245, v[248:249], off offset:576
	global_load_dword v246, v[248:249], off offset:640
	global_load_dword v247, v[248:249], off offset:704

; __device__ __forceinline__ unsigned cvt_pk_bf16(float lo, float hi) { unsigned r; asm volatile("v_cvt_pk_bf16_f32 %0, %1, %2" : "=v"(r) : "v"(lo), "v"(hi)); return r; }
; __device__ __forceinline__ float silu_f(float x) { return x * fast_rcp(1.0f + fast_exp2(-LOG2E * x)); }
;     __device__ __forceinline__ void operator()(const f32x4 (&acc)[2][2][4][2], const Unit& u, int wr, int wc, int fr, int fq) const {
;         const int row0 = u.pm * BM + wr * 64 + fr, col0 = u.pn * HALF + wc * 32 + 8 * fq;
;         float rrv[2][4];
; #pragma unroll
;         for (int ai = 0; ai < 2; ++ai)
; #pragma unroll
;             for (int m = 0; m < 4; ++m) rrv[ai][m] = rs[row0 + ai * HALF + m * 16];
; #pragma unroll
;         for (int ai = 0; ai < 2; ++ai)
; #pragma unroll
;             for (int m = 0; m < 4; ++m) {
;                 const float rr = rrv[ai][m];
;                 const f32x4 g0 = acc[ai][0][m][0] * rr, g1 = acc[ai][0][m][1] * rr, u0 = acc[ai][1][m][0] * rr, u1 = acc[ai][1][m][1] * rr;
;                 u32x4 w;
;                 w.x = cvt_pk_bf16(silu_f(g0[0]) * u0[0], silu_f(g0[1]) * u0[1]); w.y = cvt_pk_bf16(silu_f(g0[2]) * u0[2], silu_f(g0[3]) * u0[3]);
;                 w.z = cvt_pk_bf16(silu_f(g1[0]) * u1[0], silu_f(g1[1]) * u1[1]); w.w = cvt_pk_bf16(silu_f(g1[2]) * u1[2], silu_f(g1[3]) * u1[3]);
;                 *(u32x4*)(act + (size_t)(row0 + ai * HALF + m * 16) * DFF + col0) = w;
.LBB0_1553:
	v_lshl_add_u32 v162, s45, 8, v1
	v_ashrrev_i32_e32 v163, 31, v162
	v_lshl_add_u64 v[164:165], v[162:163], 2, s[8:9]
	v_mov_b32_e32 v166, v240
	v_mov_b32_e32 v142, v247
	v_or_b32_e32 v158, 16, v162
	v_ashrrev_i32_e32 v159, 31, v158
	v_lshl_add_u64 v[148:149], v[158:159], 2, s[8:9]
	v_mov_b32_e32 v160, v241
	v_or_b32_e32 v154, 32, v162
	v_ashrrev_i32_e32 v155, 31, v154
	v_or_b32_e32 v150, 48, v162
	v_lshl_add_u64 v[148:149], v[154:155], 2, s[8:9]
	v_ashrrev_i32_e32 v151, 31, v150
	v_mov_b32_e32 v156, v242
	v_mov_b32_e32 v146, v245
	v_lshl_add_u64 v[148:149], v[150:151], 2, s[8:9]
	v_mov_b32_e32 v152, v243
	v_mov_b32_e32 v144, v246
	s_movk_i32 s13, 0x1600
	v_mov_b32_e32 v148, v244
	v_lshl_or_b32 v164, s43, 7, v145
	v_ashrrev_i32_e32 v165, 31, v164
	v_add_u32_e32 v153, 0x90, v162
	v_add_u32_e32 v149, 0xb0, v162
	v_add_u32_e32 v155, 0x80, v162
	v_add_u32_e32 v151, 0xa0, v162
	s_cmp_eq_u32 s42, s40
	s_waitcnt vmcnt(0)
	v_pk_mul_f32 v[126:127], v[126:127], v[166:167] op_sel_hi:[1,0]
	v_pk_mul_f32 v[168:169], v[116:117], v[166:167] op_sel_hi:[1,0]
	v_pk_mul_f32 v[116:117], v[114:115], v[166:167] op_sel_hi:[1,0]
	v_mul_f32_e32 v114, 0xbfb8aa3b, v126
	v_mul_f32_e32 v115, 0xbfb8aa3b, v127
	v_exp_f32_e32 v114, v114
	v_exp_f32_e32 v115, v115
	v_pk_mul_f32 v[118:119], v[118:119], v[166:167] op_sel_hi:[1,0]
	v_pk_mul_f32 v[128:129], v[128:129], v[166:167] op_sel_hi:[1,0]
	v_add_f32_e32 v114, 1.0, v114
	v_add_f32_e32 v115, 1.0, v115
	v_rcp_f32_e32 v114, v114
	v_rcp_f32_e32 v115, v115
	v_pk_mul_f32 v[120:121], v[120:121], v[166:167] op_sel_hi:[1,0]
	v_pk_mul_f32 v[122:123], v[122:123], v[166:167] op_sel_hi:[1,0]
	v_mul_f32_e32 v114, v126, v114
	v_mul_f32_e32 v115, v127, v115
	v_mul_f32_e32 v114, v118, v114
	v_mul_f32_e32 v115, v119, v115
	v_cvt_pk_bf16_f32 v114, v114, v115
	v_mul_f32_e32 v115, 0xbfb8aa3b, v128
	v_mul_f32_e32 v118, 0xbfb8aa3b, v129
	v_exp_f32_e32 v115, v115
	v_exp_f32_e32 v118, v118
	v_pk_mul_f32 v[124:125], v[124:125], v[166:167] op_sel_hi:[1,0]
	v_pk_mul_f32 v[110:111], v[110:111], v[160:161] op_sel_hi:[1,0]
	v_add_f32_e32 v115, 1.0, v115
	v_add_f32_e32 v118, 1.0, v118
	v_rcp_f32_e32 v115, v115
	v_rcp_f32_e32 v118, v118
	v_pk_mul_f32 v[102:103], v[102:103], v[160:161] op_sel_hi:[1,0]
	v_pk_mul_f32 v[112:113], v[112:113], v[160:161] op_sel_hi:[1,0]
	v_mul_f32_e32 v115, v128, v115
	v_mul_f32_e32 v118, v129, v118
	v_mul_f32_e32 v115, v120, v115
	v_mul_f32_e32 v118, v121, v118
	v_cvt_pk_bf16_f32 v115, v115, v118
	v_mul_f32_e32 v118, 0xbfb8aa3b, v122
	v_exp_f32_e32 v118, v118
	v_lshlrev_b64 v[120:121], 1, v[164:165]
	v_pk_mul_f32 v[104:105], v[104:105], v[160:161] op_sel_hi:[1,0]
	v_pk_mul_f32 v[106:107], v[106:107], v[160:161] op_sel_hi:[1,0]
	v_add_f32_e32 v118, 1.0, v118
	v_rcp_f32_e32 v118, v118
	v_pk_mul_f32 v[98:99], v[98:99], v[160:161] op_sel_hi:[1,0]
	v_pk_mul_f32 v[108:109], v[108:109], v[160:161] op_sel_hi:[1,0]
	v_pk_mul_f32 v[100:101], v[100:101], v[160:161] op_sel_hi:[1,0]
	v_mul_f32_e32 v118, v122, v118
	v_mul_f32_e32 v116, v116, v118
	v_mul_f32_e32 v118, 0xbfb8aa3b, v123
	v_exp_f32_e32 v118, v118
	v_pk_mul_f32 v[94:95], v[94:95], v[156:157] op_sel_hi:[1,0]
	v_pk_mul_f32 v[86:87], v[86:87], v[156:157] op_sel_hi:[1,0]
	v_pk_mul_f32 v[96:97], v[96:97], v[156:157] op_sel_hi:[1,0]
	v_add_f32_e32 v118, 1.0, v118
	v_rcp_f32_e32 v118, v118
	v_pk_mul_f32 v[88:89], v[88:89], v[156:157] op_sel_hi:[1,0]
	v_pk_mul_f32 v[90:91], v[90:91], v[156:157] op_sel_hi:[1,0]
	v_pk_mul_f32 v[92:93], v[92:93], v[156:157] op_sel_hi:[1,0]
	v_mul_f32_e32 v118, v123, v118
	v_mul_f32_e32 v117, v117, v118
	v_cvt_pk_bf16_f32 v116, v116, v117
	v_mul_f32_e32 v117, 0xbfb8aa3b, v124
	v_mul_f32_e32 v118, 0xbfb8aa3b, v125
	v_exp_f32_e32 v117, v117
	v_exp_f32_e32 v118, v118
	v_pk_mul_f32 v[78:79], v[78:79], v[152:153] op_sel_hi:[1,0]
	v_pk_mul_f32 v[70:71], v[70:71], v[152:153] op_sel_hi:[1,0]
	v_add_f32_e32 v117, 1.0, v117
	v_add_f32_e32 v118, 1.0, v118
	v_rcp_f32_e32 v117, v117
	v_rcp_f32_e32 v118, v118
	v_pk_mul_f32 v[80:81], v[80:81], v[152:153] op_sel_hi:[1,0]
	v_pk_mul_f32 v[72:73], v[72:73], v[152:153] op_sel_hi:[1,0]
	v_mul_f32_e32 v117, v124, v117
	v_mul_f32_e32 v118, v125, v118
	v_mul_f32_e32 v117, v168, v117
	v_mul_f32_e32 v118, v169, v118
	v_cvt_pk_bf16_f32 v117, v117, v118
	v_mov_b64_e32 v[118:119], s[6:7]
	v_mad_i64_i32 v[122:123], s[20:21], v162, s13, v[118:119]
	v_lshl_add_u64 v[122:123], v[122:123], 0, v[120:121]
	global_store_dwordx4 v[122:123], v[114:117], off
	v_pk_mul_f32 v[74:75], v[74:75], v[152:153] op_sel_hi:[1,0]
	v_pk_mul_f32 v[76:77], v[76:77], v[152:153] op_sel_hi:[1,0]
	v_mul_f32_e32 v114, 0xbfb8aa3b, v110
	v_exp_f32_e32 v114, v114
	v_pk_mul_f32 v[62:63], v[62:63], v[148:149] op_sel_hi:[1,0]
	v_pk_mul_f32 v[54:55], v[54:55], v[148:149] op_sel_hi:[1,0]
	v_pk_mul_f32 v[64:65], v[64:65], v[148:149] op_sel_hi:[1,0]
	v_add_f32_e32 v114, 1.0, v114
	v_rcp_f32_e32 v114, v114
	v_pk_mul_f32 v[56:57], v[56:57], v[148:149] op_sel_hi:[1,0]
	v_pk_mul_f32 v[58:59], v[58:59], v[148:149] op_sel_hi:[1,0]
	v_pk_mul_f32 v[60:61], v[60:61], v[148:149] op_sel_hi:[1,0]
	v_mul_f32_e32 v110, v110, v114
	v_mul_f32_e32 v102, v102, v110
	v_mul_f32_e32 v110, 0xbfb8aa3b, v111
	v_exp_f32_e32 v110, v110
	v_pk_mul_f32 v[46:47], v[46:47], v[146:147] op_sel_hi:[1,0]
	v_pk_mul_f32 v[38:39], v[38:39], v[146:147] op_sel_hi:[1,0]
	v_pk_mul_f32 v[48:49], v[48:49], v[146:147] op_sel_hi:[1,0]
	v_add_f32_e32 v110, 1.0, v110
	v_rcp_f32_e32 v110, v110
	v_pk_mul_f32 v[40:41], v[40:41], v[146:147] op_sel_hi:[1,0]
	v_pk_mul_f32 v[42:43], v[42:43], v[146:147] op_sel_hi:[1,0]
	v_pk_mul_f32 v[44:45], v[44:45], v[146:147] op_sel_hi:[1,0]
	v_mul_f32_e32 v110, v111, v110
; __device__ __forceinline__ unsigned cvt_pk_bf16(float lo, float hi) { unsigned r; asm volatile("v_cvt_pk_bf16_f32 %0, %1, %2" : "=v"(r) : "v"(lo), "v"(hi)); return r; }
; __device__ __forceinline__ float silu_f(float x) { return x * fast_rcp(1.0f + fast_exp2(-LOG2E * x)); }
;     __device__ __forceinline__ void operator()(const f32x4 (&acc)[2][2][4][2], const Unit& u, int wr, int wc, int fr, int fq) const {
;     ...
;         for (int ai = 0; ai < 2; ++ai)
; #pragma unroll
;             for (int m = 0; m < 4; ++m) {
;                 const float rr = rrv[ai][m];
;                 const f32x4 g0 = acc[ai][0][m][0] * rr, g1 = acc[ai][0][m][1] * rr, u0 = acc[ai][1][m][0] * rr, u1 = acc[ai][1][m][1] * rr;
;                 u32x4 w;
;                 w.x = cvt_pk_bf16(silu_f(g0[0]) * u0[0], silu_f(g0[1]) * u0[1]); w.y = cvt_pk_bf16(silu_f(g0[2]) * u0[2], silu_f(g0[3]) * u0[3]);
;                 w.z = cvt_pk_bf16(silu_f(g1[0]) * u1[0], silu_f(g1[1]) * u1[1]); w.w = cvt_pk_bf16(silu_f(g1[2]) * u1[2], silu_f(g1[3]) * u1[3]);
;                 *(u32x4*)(act + (size_t)(row0 + ai * HALF + m * 16) * DFF + col0) = w;
	v_mul_f32_e32 v103, v103, v110
	v_cvt_pk_bf16_f32 v102, v102, v103
	v_mul_f32_e32 v103, 0xbfb8aa3b, v112
	v_exp_f32_e32 v103, v103
	v_pk_mul_f32 v[30:31], v[30:31], v[144:145] op_sel_hi:[1,0]
	v_pk_mul_f32 v[22:23], v[22:23], v[144:145] op_sel_hi:[1,0]
	v_pk_mul_f32 v[32:33], v[32:33], v[144:145] op_sel_hi:[1,0]
	v_add_f32_e32 v103, 1.0, v103
	v_rcp_f32_e32 v103, v103
	v_pk_mul_f32 v[24:25], v[24:25], v[144:145] op_sel_hi:[1,0]
	v_pk_mul_f32 v[26:27], v[26:27], v[144:145] op_sel_hi:[1,0]
	v_pk_mul_f32 v[28:29], v[28:29], v[144:145] op_sel_hi:[1,0]
	v_mul_f32_e32 v103, v112, v103
	v_mul_f32_e32 v103, v104, v103
	v_mul_f32_e32 v104, 0xbfb8aa3b, v113
	v_exp_f32_e32 v104, v104
	v_pk_mul_f32 v[14:15], v[14:15], v[142:143] op_sel_hi:[1,0]
	v_pk_mul_f32 v[6:7], v[6:7], v[142:143] op_sel_hi:[1,0]
	v_pk_mul_f32 v[16:17], v[16:17], v[142:143] op_sel_hi:[1,0]
	v_add_f32_e32 v104, 1.0, v104
	v_rcp_f32_e32 v104, v104
	v_pk_mul_f32 v[8:9], v[8:9], v[142:143] op_sel_hi:[1,0]
	v_pk_mul_f32 v[10:11], v[10:11], v[142:143] op_sel_hi:[1,0]
	v_pk_mul_f32 v[12:13], v[12:13], v[142:143] op_sel_hi:[1,0]
	v_mul_f32_e32 v104, v113, v104
	v_mul_f32_e32 v104, v105, v104
	v_cvt_pk_bf16_f32 v103, v103, v104
	v_mul_f32_e32 v104, 0xbfb8aa3b, v106
	v_exp_f32_e32 v104, v104
	s_nop 0
	v_add_f32_e32 v104, 1.0, v104
	v_rcp_f32_e32 v104, v104
	s_nop 0
	v_mul_f32_e32 v104, v106, v104
	v_mul_f32_e32 v98, v98, v104
	v_mul_f32_e32 v104, 0xbfb8aa3b, v107
	v_exp_f32_e32 v104, v104
	s_nop 0
	v_add_f32_e32 v104, 1.0, v104
	v_rcp_f32_e32 v104, v104
	s_nop 0
	v_mul_f32_e32 v104, v107, v104
	v_mul_f32_e32 v99, v99, v104
	v_cvt_pk_bf16_f32 v104, v98, v99
	v_mul_f32_e32 v98, 0xbfb8aa3b, v108
	v_mul_f32_e32 v99, 0xbfb8aa3b, v109
	v_exp_f32_e32 v98, v98
	v_exp_f32_e32 v99, v99
	v_add_f32_e32 v98, 1.0, v98
	v_add_f32_e32 v99, 1.0, v99
	v_rcp_f32_e32 v98, v98
	v_rcp_f32_e32 v99, v99
	v_mul_f32_e32 v98, v108, v98
	v_mul_f32_e32 v99, v109, v99
	v_mul_f32_e32 v98, v100, v98
	v_mul_f32_e32 v99, v101, v99
	v_cvt_pk_bf16_f32 v105, v98, v99
	v_mad_i64_i32 v[98:99], s[20:21], v158, s13, v[118:119]
	v_lshl_add_u64 v[98:99], v[98:99], 0, v[120:121]
	global_store_dwordx4 v[98:99], v[102:105], off
	v_pk_mul_f32 v[98:99], v[84:85], v[156:157] op_sel_hi:[1,0]
	v_pk_mul_f32 v[84:85], v[82:83], v[156:157] op_sel_hi:[1,0]
	v_mul_f32_e32 v82, 0xbfb8aa3b, v94
	v_mul_f32_e32 v83, 0xbfb8aa3b, v95
	v_exp_f32_e32 v82, v82
	v_exp_f32_e32 v83, v83
	v_add_f32_e32 v82, 1.0, v82
	v_add_f32_e32 v83, 1.0, v83
	v_rcp_f32_e32 v82, v82
	v_rcp_f32_e32 v83, v83
	v_mul_f32_e32 v82, v94, v82
	v_mul_f32_e32 v83, v95, v83
	v_mul_f32_e32 v82, v86, v82
	v_mul_f32_e32 v83, v87, v83
	v_cvt_pk_bf16_f32 v82, v82, v83
	v_mul_f32_e32 v83, 0xbfb8aa3b, v96
	v_mul_f32_e32 v86, 0xbfb8aa3b, v97
	v_exp_f32_e32 v83, v83
	v_exp_f32_e32 v86, v86
	v_add_f32_e32 v83, 1.0, v83
	v_add_f32_e32 v86, 1.0, v86
	v_rcp_f32_e32 v83, v83
	v_rcp_f32_e32 v86, v86
	v_mul_f32_e32 v83, v96, v83
	v_mul_f32_e32 v86, v97, v86
	v_mul_f32_e32 v83, v88, v83
	v_mul_f32_e32 v86, v89, v86
	v_cvt_pk_bf16_f32 v83, v83, v86
	v_mul_f32_e32 v86, 0xbfb8aa3b, v90
	v_exp_f32_e32 v86, v86
	s_nop 0
	v_add_f32_e32 v86, 1.0, v86
	v_rcp_f32_e32 v86, v86
	s_nop 0
	v_mul_f32_e32 v86, v90, v86
	v_mul_f32_e32 v84, v84, v86
	v_mul_f32_e32 v86, 0xbfb8aa3b, v91
	v_exp_f32_e32 v86, v86
	s_nop 0
	v_add_f32_e32 v86, 1.0, v86
	v_rcp_f32_e32 v86, v86
	s_nop 0
	v_mul_f32_e32 v86, v91, v86
	v_mul_f32_e32 v85, v85, v86
	v_cvt_pk_bf16_f32 v84, v84, v85
	v_mul_f32_e32 v85, 0xbfb8aa3b, v92
	v_mul_f32_e32 v86, 0xbfb8aa3b, v93
	v_exp_f32_e32 v85, v85
	v_exp_f32_e32 v86, v86
	v_add_f32_e32 v85, 1.0, v85
	v_add_f32_e32 v86, 1.0, v86
	v_rcp_f32_e32 v85, v85
	v_rcp_f32_e32 v86, v86
	v_mul_f32_e32 v85, v92, v85
	v_mul_f32_e32 v86, v93, v86
	v_mul_f32_e32 v85, v98, v85
	v_mul_f32_e32 v86, v99, v86
	v_cvt_pk_bf16_f32 v85, v85, v86
	v_mad_i64_i32 v[86:87], s[20:21], v154, s13, v[118:119]
	v_lshl_add_u64 v[86:87], v[86:87], 0, v[120:121]
	global_store_dwordx4 v[86:87], v[82:85], off
	s_nop 1
	v_pk_mul_f32 v[82:83], v[68:69], v[152:153] op_sel_hi:[1,0]
	v_pk_mul_f32 v[68:69], v[66:67], v[152:153] op_sel_hi:[1,0]
	v_mul_f32_e32 v66, 0xbfb8aa3b, v78
	v_mul_f32_e32 v67, 0xbfb8aa3b, v79
	v_exp_f32_e32 v66, v66
	v_exp_f32_e32 v67, v67
	v_add_f32_e32 v66, 1.0, v66
	v_add_f32_e32 v67, 1.0, v67
	v_rcp_f32_e32 v66, v66
	v_rcp_f32_e32 v67, v67
	v_mul_f32_e32 v66, v78, v66
	v_mul_f32_e32 v67, v79, v67
	v_mul_f32_e32 v66, v70, v66
	v_mul_f32_e32 v67, v71, v67
	v_cvt_pk_bf16_f32 v66, v66, v67
	v_mul_f32_e32 v67, 0xbfb8aa3b, v80
	v_mul_f32_e32 v70, 0xbfb8aa3b, v81
	v_exp_f32_e32 v67, v67
	v_exp_f32_e32 v70, v70
	v_add_f32_e32 v67, 1.0, v67
	v_add_f32_e32 v70, 1.0, v70
	v_rcp_f32_e32 v67, v67
	v_rcp_f32_e32 v70, v70
	v_mul_f32_e32 v67, v80, v67
	v_mul_f32_e32 v70, v81, v70
	v_mul_f32_e32 v67, v72, v67
	v_mul_f32_e32 v70, v73, v70
	v_cvt_pk_bf16_f32 v67, v67, v70
	v_mul_f32_e32 v70, 0xbfb8aa3b, v74
	v_exp_f32_e32 v70, v70
	s_nop 0
	v_add_f32_e32 v70, 1.0, v70
	v_rcp_f32_e32 v70, v70
	s_nop 0
	v_mul_f32_e32 v70, v74, v70
	v_mul_f32_e32 v68, v68, v70
	v_mul_f32_e32 v70, 0xbfb8aa3b, v75
	v_exp_f32_e32 v70, v70
	s_nop 0
	v_add_f32_e32 v70, 1.0, v70
	v_rcp_f32_e32 v70, v70
	s_nop 0
	v_mul_f32_e32 v70, v75, v70
	v_mul_f32_e32 v69, v69, v70
	v_cvt_pk_bf16_f32 v68, v68, v69
	v_mul_f32_e32 v69, 0xbfb8aa3b, v76
	v_mul_f32_e32 v70, 0xbfb8aa3b, v77
	v_exp_f32_e32 v69, v69
	v_exp_f32_e32 v70, v70
	v_add_f32_e32 v69, 1.0, v69
	v_add_f32_e32 v70, 1.0, v70
	v_rcp_f32_e32 v69, v69
	v_rcp_f32_e32 v70, v70
	v_mul_f32_e32 v69, v76, v69
	v_mul_f32_e32 v70, v77, v70
	v_mul_f32_e32 v69, v82, v69
	v_mul_f32_e32 v70, v83, v70
	v_cvt_pk_bf16_f32 v69, v69, v70
; __device__ __forceinline__ unsigned cvt_pk_bf16(float lo, float hi) { unsigned r; asm volatile("v_cvt_pk_bf16_f32 %0, %1, %2" : "=v"(r) : "v"(lo), "v"(hi)); return r; }
; __device__ __forceinline__ float silu_f(float x) { return x * fast_rcp(1.0f + fast_exp2(-LOG2E * x)); }
;     __device__ __forceinline__ void operator()(const f32x4 (&acc)[2][2][4][2], const Unit& u, int wr, int wc, int fr, int fq) const {
;     ...
;         for (int ai = 0; ai < 2; ++ai)
; #pragma unroll
;             for (int m = 0; m < 4; ++m) {
;                 const float rr = rrv[ai][m];
;                 const f32x4 g0 = acc[ai][0][m][0] * rr, g1 = acc[ai][0][m][1] * rr, u0 = acc[ai][1][m][0] * rr, u1 = acc[ai][1][m][1] * rr;
;                 u32x4 w;
;                 w.x = cvt_pk_bf16(silu_f(g0[0]) * u0[0], silu_f(g0[1]) * u0[1]); w.y = cvt_pk_bf16(silu_f(g0[2]) * u0[2], silu_f(g0[3]) * u0[3]);
;                 w.z = cvt_pk_bf16(silu_f(g1[0]) * u1[0], silu_f(g1[1]) * u1[1]); w.w = cvt_pk_bf16(silu_f(g1[2]) * u1[2], silu_f(g1[3]) * u1[3]);
;                 *(u32x4*)(act + (size_t)(row0 + ai * HALF + m * 16) * DFF + col0) = w;
	v_mad_i64_i32 v[70:71], s[20:21], v150, s13, v[118:119]
	v_lshl_add_u64 v[70:71], v[70:71], 0, v[120:121]
	global_store_dwordx4 v[70:71], v[66:69], off
	s_nop 1
	v_pk_mul_f32 v[66:67], v[52:53], v[148:149] op_sel_hi:[1,0]
	v_pk_mul_f32 v[52:53], v[50:51], v[148:149] op_sel_hi:[1,0]
	v_mul_f32_e32 v50, 0xbfb8aa3b, v62
	v_mul_f32_e32 v51, 0xbfb8aa3b, v63
	v_exp_f32_e32 v50, v50
	v_exp_f32_e32 v51, v51
	v_add_f32_e32 v50, 1.0, v50
	v_add_f32_e32 v51, 1.0, v51
	v_rcp_f32_e32 v50, v50
	v_rcp_f32_e32 v51, v51
	v_mul_f32_e32 v50, v62, v50
	v_mul_f32_e32 v51, v63, v51
	v_mul_f32_e32 v50, v54, v50
	v_mul_f32_e32 v51, v55, v51
	v_cvt_pk_bf16_f32 v50, v50, v51
	v_mul_f32_e32 v51, 0xbfb8aa3b, v64
	v_mul_f32_e32 v54, 0xbfb8aa3b, v65
	v_exp_f32_e32 v51, v51
	v_exp_f32_e32 v54, v54
	v_add_f32_e32 v51, 1.0, v51
	v_add_f32_e32 v54, 1.0, v54
	v_rcp_f32_e32 v51, v51
	v_rcp_f32_e32 v54, v54
	v_mul_f32_e32 v51, v64, v51
	v_mul_f32_e32 v54, v65, v54
	v_mul_f32_e32 v51, v56, v51
	v_mul_f32_e32 v54, v57, v54
	v_cvt_pk_bf16_f32 v51, v51, v54
	v_mul_f32_e32 v54, 0xbfb8aa3b, v58
	v_exp_f32_e32 v54, v54
	s_nop 0
	v_add_f32_e32 v54, 1.0, v54
	v_rcp_f32_e32 v54, v54
	s_nop 0
	v_mul_f32_e32 v54, v58, v54
	v_mul_f32_e32 v52, v52, v54
	v_mul_f32_e32 v54, 0xbfb8aa3b, v59
	v_exp_f32_e32 v54, v54
	s_nop 0
	v_add_f32_e32 v54, 1.0, v54
	v_rcp_f32_e32 v54, v54
	s_nop 0
	v_mul_f32_e32 v54, v59, v54
	v_mul_f32_e32 v53, v53, v54
	v_cvt_pk_bf16_f32 v52, v52, v53
	v_mul_f32_e32 v53, 0xbfb8aa3b, v60
	v_mul_f32_e32 v54, 0xbfb8aa3b, v61
	v_exp_f32_e32 v53, v53
	v_exp_f32_e32 v54, v54
	v_add_f32_e32 v53, 1.0, v53
	v_add_f32_e32 v54, 1.0, v54
	v_rcp_f32_e32 v53, v53
	v_rcp_f32_e32 v54, v54
	v_mul_f32_e32 v53, v60, v53
	v_mul_f32_e32 v54, v61, v54
	v_mul_f32_e32 v53, v66, v53
	v_mul_f32_e32 v54, v67, v54
	v_cvt_pk_bf16_f32 v53, v53, v54
	v_mad_i64_i32 v[54:55], s[20:21], v155, s13, v[118:119]
	v_lshl_add_u64 v[54:55], v[54:55], 0, v[120:121]
	global_store_dwordx4 v[54:55], v[50:53], off
	s_nop 1
	v_pk_mul_f32 v[50:51], v[36:37], v[146:147] op_sel_hi:[1,0]
	v_pk_mul_f32 v[36:37], v[34:35], v[146:147] op_sel_hi:[1,0]
	v_mul_f32_e32 v34, 0xbfb8aa3b, v46
	v_mul_f32_e32 v35, 0xbfb8aa3b, v47
	v_exp_f32_e32 v34, v34
	v_exp_f32_e32 v35, v35
	v_add_f32_e32 v34, 1.0, v34
	v_add_f32_e32 v35, 1.0, v35
	v_rcp_f32_e32 v34, v34
	v_rcp_f32_e32 v35, v35
	v_mul_f32_e32 v34, v46, v34
	v_mul_f32_e32 v35, v47, v35
	v_mul_f32_e32 v34, v38, v34
	v_mul_f32_e32 v35, v39, v35
	v_cvt_pk_bf16_f32 v34, v34, v35
	v_mul_f32_e32 v35, 0xbfb8aa3b, v48
	v_mul_f32_e32 v38, 0xbfb8aa3b, v49
	v_exp_f32_e32 v35, v35
	v_exp_f32_e32 v38, v38
	v_add_f32_e32 v35, 1.0, v35
	v_add_f32_e32 v38, 1.0, v38
	v_rcp_f32_e32 v35, v35
	v_rcp_f32_e32 v38, v38
	v_mul_f32_e32 v35, v48, v35
	v_mul_f32_e32 v38, v49, v38
	v_mul_f32_e32 v35, v40, v35
	v_mul_f32_e32 v38, v41, v38
	v_cvt_pk_bf16_f32 v35, v35, v38
	v_mul_f32_e32 v38, 0xbfb8aa3b, v42
	v_exp_f32_e32 v38, v38
	s_nop 0
	v_add_f32_e32 v38, 1.0, v38
	v_rcp_f32_e32 v38, v38
	s_nop 0
	v_mul_f32_e32 v38, v42, v38
	v_mul_f32_e32 v36, v36, v38
	v_mul_f32_e32 v38, 0xbfb8aa3b, v43
	v_exp_f32_e32 v38, v38
	s_nop 0
	v_add_f32_e32 v38, 1.0, v38
	v_rcp_f32_e32 v38, v38
	s_nop 0
	v_mul_f32_e32 v38, v43, v38
	v_mul_f32_e32 v37, v37, v38
	v_cvt_pk_bf16_f32 v36, v36, v37
	v_mul_f32_e32 v37, 0xbfb8aa3b, v44
	v_mul_f32_e32 v38, 0xbfb8aa3b, v45
	v_exp_f32_e32 v37, v37
	v_exp_f32_e32 v38, v38
	v_add_f32_e32 v37, 1.0, v37
	v_add_f32_e32 v38, 1.0, v38
	v_rcp_f32_e32 v37, v37
	v_rcp_f32_e32 v38, v38
	v_mul_f32_e32 v37, v44, v37
	v_mul_f32_e32 v38, v45, v38
	v_mul_f32_e32 v37, v50, v37
	v_mul_f32_e32 v38, v51, v38
	v_cvt_pk_bf16_f32 v37, v37, v38
	v_mad_i64_i32 v[38:39], s[20:21], v153, s13, v[118:119]
	v_lshl_add_u64 v[38:39], v[38:39], 0, v[120:121]
; __device__ __forceinline__ unsigned cvt_pk_bf16(float lo, float hi) { unsigned r; asm volatile("v_cvt_pk_bf16_f32 %0, %1, %2" : "=v"(r) : "v"(lo), "v"(hi)); return r; }
; __device__ __forceinline__ float silu_f(float x) { return x * fast_rcp(1.0f + fast_exp2(-LOG2E * x)); }
; #define PG8_BAR __builtin_amdgcn_s_barrier()
;     __device__ __forceinline__ void operator()(const f32x4 (&acc)[2][2][4][2], const Unit& u, int wr, int wc, int fr, int fq) const {
;     ...
;         for (int ai = 0; ai < 2; ++ai)
; #pragma unroll
;             for (int m = 0; m < 4; ++m) {
;                 const float rr = rrv[ai][m];
;                 const f32x4 g0 = acc[ai][0][m][0] * rr, g1 = acc[ai][0][m][1] * rr, u0 = acc[ai][1][m][0] * rr, u1 = acc[ai][1][m][1] * rr;
;                 u32x4 w;
;                 w.x = cvt_pk_bf16(silu_f(g0[0]) * u0[0], silu_f(g0[1]) * u0[1]); w.y = cvt_pk_bf16(silu_f(g0[2]) * u0[2], silu_f(g0[3]) * u0[3]);
;                 w.z = cvt_pk_bf16(silu_f(g1[0]) * u1[0], silu_f(g1[1]) * u1[1]); w.w = cvt_pk_bf16(silu_f(g1[2]) * u1[2], silu_f(g1[3]) * u1[3]);
;                 *(u32x4*)(act + (size_t)(row0 + ai * HALF + m * 16) * DFF + col0) = w;
; template <class Epi>
; __device__ __forceinline__ void gemm_phase(LAS unsigned char* lds, const Gemm g, const StaticOrder& S, const Epi& E) {
;     ...
;         if (!has_next) break;
; #pragma unroll
;         for (int a = 0; a < 2; ++a)
; #pragma unroll
;             for (int b = 0; b < 2; ++b)
; #pragma unroll
;                 for (int m = 0; m < 4; ++m)
; #pragma unroll
;                     for (int n = 0; n < 2; ++n) acc[a][b][m][n] = (f32x4){0.f, 0.f, 0.f, 0.f};
;         cur = nxt; cA = nA; cB = nB; ++ui;
;         if (wr == 1) PG8_BAR;
;     }
	global_store_dwordx4 v[38:39], v[34:37], off
	s_nop 1
	v_pk_mul_f32 v[34:35], v[20:21], v[144:145] op_sel_hi:[1,0]
	v_pk_mul_f32 v[20:21], v[18:19], v[144:145] op_sel_hi:[1,0]
	v_mul_f32_e32 v18, 0xbfb8aa3b, v30
	v_mul_f32_e32 v19, 0xbfb8aa3b, v31
	v_exp_f32_e32 v18, v18
	v_exp_f32_e32 v19, v19
	v_add_f32_e32 v18, 1.0, v18
	v_add_f32_e32 v19, 1.0, v19
	v_rcp_f32_e32 v18, v18
	v_rcp_f32_e32 v19, v19
	v_mul_f32_e32 v18, v30, v18
	v_mul_f32_e32 v19, v31, v19
	v_mul_f32_e32 v18, v22, v18
	v_mul_f32_e32 v19, v23, v19
	v_cvt_pk_bf16_f32 v18, v18, v19
	v_mul_f32_e32 v19, 0xbfb8aa3b, v32
	v_mul_f32_e32 v22, 0xbfb8aa3b, v33
	v_exp_f32_e32 v19, v19
	v_exp_f32_e32 v22, v22
	v_add_f32_e32 v19, 1.0, v19
	v_add_f32_e32 v22, 1.0, v22
	v_rcp_f32_e32 v19, v19
	v_rcp_f32_e32 v22, v22
	v_mul_f32_e32 v19, v32, v19
	v_mul_f32_e32 v22, v33, v22
	v_mul_f32_e32 v19, v24, v19
	v_mul_f32_e32 v22, v25, v22
	v_cvt_pk_bf16_f32 v19, v19, v22
	v_mul_f32_e32 v22, 0xbfb8aa3b, v26
	v_exp_f32_e32 v22, v22
	s_nop 0
	v_add_f32_e32 v22, 1.0, v22
	v_rcp_f32_e32 v22, v22
	s_nop 0
	v_mul_f32_e32 v22, v26, v22
	v_mul_f32_e32 v20, v20, v22
	v_mul_f32_e32 v22, 0xbfb8aa3b, v27
	v_exp_f32_e32 v22, v22
	s_nop 0
	v_add_f32_e32 v22, 1.0, v22
	v_rcp_f32_e32 v22, v22
	s_nop 0
	v_mul_f32_e32 v22, v27, v22
	v_mul_f32_e32 v21, v21, v22
	v_cvt_pk_bf16_f32 v20, v20, v21
	v_mul_f32_e32 v21, 0xbfb8aa3b, v28
	v_mul_f32_e32 v22, 0xbfb8aa3b, v29
	v_exp_f32_e32 v21, v21
	v_exp_f32_e32 v22, v22
	v_add_f32_e32 v21, 1.0, v21
	v_add_f32_e32 v22, 1.0, v22
	v_rcp_f32_e32 v21, v21
	v_rcp_f32_e32 v22, v22
	v_mul_f32_e32 v21, v28, v21
	v_mul_f32_e32 v22, v29, v22
	v_mul_f32_e32 v21, v34, v21
	v_mul_f32_e32 v22, v35, v22
	v_cvt_pk_bf16_f32 v21, v21, v22
	v_mad_i64_i32 v[22:23], s[20:21], v151, s13, v[118:119]
	v_lshl_add_u64 v[22:23], v[22:23], 0, v[120:121]
	global_store_dwordx4 v[22:23], v[18:21], off
	s_nop 1
	v_pk_mul_f32 v[18:19], v[4:5], v[142:143] op_sel_hi:[1,0]
	v_pk_mul_f32 v[4:5], v[2:3], v[142:143] op_sel_hi:[1,0]
	v_mul_f32_e32 v2, 0xbfb8aa3b, v14
	v_mul_f32_e32 v3, 0xbfb8aa3b, v15
	v_exp_f32_e32 v2, v2
	v_exp_f32_e32 v3, v3
	v_add_f32_e32 v2, 1.0, v2
	v_add_f32_e32 v3, 1.0, v3
	v_rcp_f32_e32 v2, v2
	v_rcp_f32_e32 v3, v3
	v_mul_f32_e32 v2, v14, v2
	v_mul_f32_e32 v3, v15, v3
	v_mul_f32_e32 v2, v6, v2
	v_mul_f32_e32 v3, v7, v3
	v_cvt_pk_bf16_f32 v2, v2, v3
	v_mul_f32_e32 v3, 0xbfb8aa3b, v16
	v_mul_f32_e32 v6, 0xbfb8aa3b, v17
	v_exp_f32_e32 v3, v3
	v_exp_f32_e32 v6, v6
	v_add_f32_e32 v3, 1.0, v3
	v_add_f32_e32 v6, 1.0, v6
	v_rcp_f32_e32 v3, v3
	v_rcp_f32_e32 v6, v6
	v_mul_f32_e32 v3, v16, v3
	v_mul_f32_e32 v6, v17, v6
	v_mul_f32_e32 v3, v8, v3
	v_mul_f32_e32 v6, v9, v6
	v_cvt_pk_bf16_f32 v3, v3, v6
	v_mul_f32_e32 v6, 0xbfb8aa3b, v10
	v_exp_f32_e32 v6, v6
	s_nop 0
	v_add_f32_e32 v6, 1.0, v6
	v_rcp_f32_e32 v6, v6
	s_nop 0
	v_mul_f32_e32 v6, v10, v6
	v_mul_f32_e32 v4, v4, v6
	v_mul_f32_e32 v6, 0xbfb8aa3b, v11
	v_exp_f32_e32 v6, v6
	s_nop 0
	v_add_f32_e32 v6, 1.0, v6
	v_rcp_f32_e32 v6, v6
	s_nop 0
	v_mul_f32_e32 v6, v11, v6
	v_mul_f32_e32 v5, v5, v6
	v_cvt_pk_bf16_f32 v4, v4, v5
	v_mul_f32_e32 v5, 0xbfb8aa3b, v12
	v_mul_f32_e32 v6, 0xbfb8aa3b, v13
	v_exp_f32_e32 v5, v5
	v_exp_f32_e32 v6, v6
	v_add_f32_e32 v5, 1.0, v5
	v_add_f32_e32 v6, 1.0, v6
	v_rcp_f32_e32 v5, v5
	v_rcp_f32_e32 v6, v6
	v_mul_f32_e32 v5, v12, v5
	v_mul_f32_e32 v6, v13, v6
	v_mul_f32_e32 v5, v18, v5
	v_mul_f32_e32 v6, v19, v6
	v_cvt_pk_bf16_f32 v5, v5, v6
	v_mad_i64_i32 v[6:7], s[20:21], v149, s13, v[118:119]
	v_lshl_add_u64 v[6:7], v[6:7], 0, v[120:121]
	s_mov_b64 s[20:21], -1
	global_store_dwordx4 v[6:7], v[2:5], off
	s_cbranch_scc1 .LBB0_1546
	s_andn2_b64 vcc, exec, s[4:5]
	s_cbranch_vccnz .LBB0_1545
	s_barrier
	s_branch .LBB0_1545
